# attn loop: K fragments triple-buffered (reads issued three steps ahead)
# baseline (speedup 1.0000x reference)
; #define SBAR() __builtin_amdgcn_sched_barrier(0)
; #define SLOAD(i, k0) do { const char* vb_ = (const char*)Vh + (size_t)(k0) * (LDV * 2); const char* kb_ = (const char*)Kh + (size_t)(k0) * (LDKK * 2); \
;     sr_[i].vs0 = *(const bf16x8*)(vb_ + voff); sr_[i].vs1 = *(const bf16x8*)(vb_ + 32 * LDV * 2 + voff); \
;     sr_[i].ks0 = *(const bf16x8*)(kb_ + koff); sr_[i].ks1 = *(const bf16x8*)(kb_ + 32 * LDKK * 2 + koff); } while (0)
; __device__ __forceinline__ void finishSM(f32x16& p0, f32x16& p1, float alpha, float& l_reg, bf16x8& pa0, bf16x8& pa1, bf16x8& pa2, bf16x8& pa3) {
;   for (int r = 0; r < 16; ++r) p1[r] = __builtin_amdgcn_exp2f(p1[r]);
;   float ps = 0; for (int r = 0; r < 16; ++r) ps += p0[r]; for (int r = 0; r < 16; ++r) ps += p1[r];
;   { auto rr = __builtin_amdgcn_permlane32_swap(__float_as_uint(ps), __float_as_uint(ps), false, false);
;     ps = __uint_as_float(rr[0]) + __uint_as_float(rr[1]); }
;   l_reg = l_reg * alpha + ps;
;   ATT_PK4(p0, 0, pa0); ATT_PK4(p0, 8, pa1); ATT_PK4(p1, 0, pa2); ATT_PK4(p1, 8, pa3);
; }
; __device__ __forceinline__ void qkt(f32x16& p0, f32x16& p1, const bf16_t* Ks, const bf16x8* qr, int r32, int hi) {
;   p0 = f32x16{}; p1 = f32x16{};
;   for (int d0 = 0; d0 < 8; ++d0) { int cb = (d0 * 16 + hi * 8) * 2;
;     bf16x8 b0 = *reinterpret_cast<const bf16x8*>((const char*)Ks + KSWZ(r32, cb));
;     bf16x8 b1 = *reinterpret_cast<const bf16x8*>((const char*)Ks + KSWZ(32 + r32, cb));
;     p0 = __builtin_amdgcn_mfma_f32_32x32x16_bf16(b0, qr[d0], p0, 0, 0, 0);
;     p1 = __builtin_amdgcn_mfma_f32_32x32x16_bf16(b1, qr[d0], p1, 0, 0, 0); }
; template <bool FAST> __device__ __forceinline__ void attn_dense_body(const bf16_t* __restrict__ Qb, const bf16_t* __restrict__ Kh, const bf16_t* __restrict__ Vh, ...
;     ...
;     SBAR(); qkt(pB0, pB1, (bf16_t*)((char*)K_lds + SHM_K), qr, r32, hi);
;     fsm<FAST>(pA0, pA1, alA, l_reg, pa0, pa1, pa2, pa3); SBAR();
;     SLOAD(SO, (j + 2) * KVBLK); SBAR();
;     pv_d0(o, vb0, pa0, pa1, pa2, pa3); psm<FAST>(pB0, pB1, m_reg, mnB, alB);
.Lattn_h1:
	ds_read_b128 v[184:187], v219 offset:49152
	ds_read_b128 v[190:193], v219 offset:57344
	s_waitcnt lgkmcnt(5)
	v_mfma_f32_32x32x16_bf16 v[98:113], v[172:175], v[144:147], 0
	v_exp_f32_e32 v239, v66
	v_exp_f32_e32 v240, v67
	v_add_f32_e32 v202, 0, v229
	s_waitcnt lgkmcnt(4)
	v_mfma_f32_32x32x16_bf16 v[82:97], v[176:179], v[144:147], 0
	ds_read_b128 v[172:175], v216 offset:49152
	ds_read_b128 v[176:179], v216 offset:57344
	v_exp_f32_e32 v241, v68
	v_exp_f32_e32 v242, v69
	v_add_f32_e32 v202, v230, v202
	s_waitcnt lgkmcnt(5)
	v_mfma_f32_32x32x16_bf16 v[98:113], v[164:167], v[140:143], v[98:113]
	v_exp_f32_e32 v243, v70
	v_exp_f32_e32 v244, v71
	v_add_f32_e32 v202, v231, v202
	s_waitcnt lgkmcnt(4)
	v_mfma_f32_32x32x16_bf16 v[82:97], v[168:171], v[140:143], v[82:97]
	ds_read_b128 v[164:167], v215 offset:49152
	ds_read_b128 v[168:171], v215 offset:57344
	v_exp_f32_e32 v245, v72
	v_exp_f32_e32 v246, v73
	v_add_f32_e32 v202, v233, v202
	s_waitcnt lgkmcnt(5)
	v_mfma_f32_32x32x16_bf16 v[98:113], v[184:187], v[136:139], v[98:113]
	v_cvt_pk_bf16_f32 v66, v229, v230
	v_cvt_pk_bf16_f32 v67, v231, v233
	v_cvt_pk_bf16_f32 v68, v234, v236
	v_cvt_pk_bf16_f32 v69, v232, v235
	v_add_f32_e32 v202, v234, v202
	s_waitcnt lgkmcnt(4)
	v_mfma_f32_32x32x16_bf16 v[82:97], v[190:193], v[136:139], v[82:97]
	ds_read_b128 v[184:187], v214 offset:49152
	ds_read_b128 v[190:193], v214 offset:57344
	v_add_f32_e32 v202, v236, v202
	v_add_f32_e32 v202, v232, v202
	v_permlane32_swap_b32_e32 v66, v68
	v_permlane32_swap_b32_e32 v67, v69
	v_exp_f32_e32 v247, v74
	s_waitcnt lgkmcnt(5)
	v_mfma_f32_32x32x16_bf16 v[98:113], v[172:175], v[132:135], v[98:113]
	v_exp_f32_e32 v248, v75
	v_add_f32_e32 v202, v235, v202
	v_add_f32_e32 v202, v199, v202
	v_add_f32_e32 v202, v200, v202
	s_waitcnt lgkmcnt(4)
	v_mfma_f32_32x32x16_bf16 v[82:97], v[176:179], v[132:135], v[82:97]
	ds_read_b128 v[172:175], v213 offset:49152
	ds_read_b128 v[176:179], v213 offset:57344
	v_cvt_pk_bf16_f32 v70, v199, v200
	v_cvt_pk_bf16_f32 v71, v201, v227
	v_cvt_pk_bf16_f32 v72, v198, v225
	v_cvt_pk_bf16_f32 v73, v226, v228
	v_add_f32_e32 v202, v201, v202
	s_waitcnt lgkmcnt(5)
	v_mfma_f32_32x32x16_bf16 v[98:113], v[164:167], v[128:131], v[98:113]
	v_add_f32_e32 v202, v227, v202
	v_add_f32_e32 v202, v198, v202
	v_permlane32_swap_b32_e32 v70, v72
	v_permlane32_swap_b32_e32 v71, v73
	s_waitcnt vmcnt(0)
	ds_write_b128 v220, v[156:159] offset:32768
	ds_write_b128 v222, v[160:163] offset:32768
	s_waitcnt lgkmcnt(6)
	v_mfma_f32_32x32x16_bf16 v[82:97], v[168:171], v[128:131], v[82:97]
	ds_read_b128 v[164:167], v224 offset:49152
	ds_read_b128 v[168:171], v224 offset:57344
	v_exp_f32_e32 v249, v76
	v_exp_f32_e32 v250, v77
	v_add_f32_e32 v202, v225, v202
	s_waitcnt lgkmcnt(7)
	v_mfma_f32_32x32x16_bf16 v[98:113], v[184:187], v[124:127], v[98:113]
	v_exp_f32_e32 v251, v78
	v_exp_f32_e32 v252, v79
	v_add_f32_e32 v202, v226, v202
	s_waitcnt lgkmcnt(6)
	v_mfma_f32_32x32x16_bf16 v[82:97], v[190:193], v[124:127], v[82:97]
	v_exp_f32_e32 v182, v80
	v_exp_f32_e32 v183, v81
	v_add_f32_e32 v202, v228, v202
	s_waitcnt lgkmcnt(5)
	v_mfma_f32_32x32x16_bf16 v[98:113], v[172:175], v[120:123], v[98:113]
	v_cvt_pk_bf16_f32 v74, v239, v240
	v_cvt_pk_bf16_f32 v75, v241, v242
	v_cvt_pk_bf16_f32 v76, v243, v244
	v_cvt_pk_bf16_f32 v77, v245, v246
	s_waitcnt lgkmcnt(4)
	v_mfma_f32_32x32x16_bf16 v[82:97], v[176:179], v[120:123], v[82:97]
	v_cvt_pk_bf16_f32 v78, v247, v248
	v_cvt_pk_bf16_f32 v79, v249, v250
	v_permlane32_swap_b32_e32 v74, v76
	v_permlane32_swap_b32_e32 v75, v77
	ds_read_b64_tr_b16 v[198:199], v180 offset:0
	ds_read_b64_tr_b16 v[200:201], v180 offset:2048
	s_waitcnt lgkmcnt(3)
	v_mfma_f32_32x32x16_bf16 v[98:113], v[164:167], v[116:119], v[98:113]
	v_cvt_pk_bf16_f32 v80, v251, v252
	v_cvt_pk_bf16_f32 v81, v182, v183
	ds_read_b64_tr_b16 v[226:227], v180 offset:4096
	ds_read_b64_tr_b16 v[228:229], v180 offset:6144
	ds_read_b64_tr_b16 v[230:231], v180 offset:8192
	ds_read_b64_tr_b16 v[232:233], v180 offset:10240
	s_waitcnt lgkmcnt(6)
	v_mfma_f32_32x32x16_bf16 v[82:97], v[168:171], v[116:119], v[82:97]
	ds_read_b64_tr_b16 v[234:235], v180 offset:12288
	ds_read_b64_tr_b16 v[236:237], v180 offset:14336
	v_permlane32_swap_b32_e32 v78, v80
	v_permlane32_swap_b32_e32 v79, v81
	s_waitcnt lgkmcnt(6)
	v_mfma_f32_32x32x16_bf16 v[2:17], v[66:69], v[198:201], v[2:17]
	ds_read_b64_tr_b16 v[198:199], v180 offset:512
	ds_read_b64_tr_b16 v[200:201], v180 offset:2560
	v_add_f32_e32 v202, v239, v202
	v_exp_f32_e32 v239, v98
	v_lshl_add_u64 v[188:189], v[196:197], 0, s[48:49]
	v_lshl_add_u64 v[186:187], v[194:195], 0, s[48:49]
	s_waitcnt lgkmcnt(6)
	v_mfma_f32_32x32x16_bf16 v[2:17], v[70:73], v[226:229], v[2:17]
	ds_read_b64_tr_b16 v[226:227], v180 offset:4608
	ds_read_b64_tr_b16 v[228:229], v180 offset:6656
	v_add_f32_e32 v202, v240, v202
	v_exp_f32_e32 v240, v99
	v_add_co_u32_e32 v164, vcc, s62, v188
	s_mov_b32 s3, 0x5f238000
	s_waitcnt lgkmcnt(6)
	v_mfma_f32_32x32x16_bf16 v[2:17], v[74:77], v[230:233], v[2:17]
	ds_read_b64_tr_b16 v[230:231], v180 offset:8704
	ds_read_b64_tr_b16 v[232:233], v180 offset:10752
	v_add_f32_e32 v202, v241, v202
	v_exp_f32_e32 v241, v100
	v_addc_co_u32_e32 v165, vcc, 0, v189, vcc
	v_add_co_u32_e32 v168, vcc, s59, v188
	s_waitcnt lgkmcnt(6)
	v_mfma_f32_32x32x16_bf16 v[2:17], v[78:81], v[234:237], v[2:17]
	ds_read_b64_tr_b16 v[234:235], v180 offset:12800
	ds_read_b64_tr_b16 v[236:237], v180 offset:14848
	v_add_f32_e32 v202, v242, v202
	v_exp_f32_e32 v242, v101
	global_load_dwordx4 v[164:167], v[164:165], off offset:1024
	v_addc_co_u32_e32 v169, vcc, 0, v189, vcc
	v_add_co_u32_e32 v172, vcc, s24, v186
	s_waitcnt lgkmcnt(6)
; #define SBAR() __builtin_amdgcn_sched_barrier(0)
; #define SLOAD(i, k0) do { const char* vb_ = (const char*)Vh + (size_t)(k0) * (LDV * 2); const char* kb_ = (const char*)Kh + (size_t)(k0) * (LDKK * 2); \
;     sr_[i].vs0 = *(const bf16x8*)(vb_ + voff); sr_[i].vs1 = *(const bf16x8*)(vb_ + 32 * LDV * 2 + voff); \
;     sr_[i].ks0 = *(const bf16x8*)(kb_ + koff); sr_[i].ks1 = *(const bf16x8*)(kb_ + 32 * LDKK * 2 + koff); } while (0)
; #define SWAIT() asm volatile("s_waitcnt vmcnt(4)" ::: "memory")
; template <int D0> __device__ __forceinline__ void pv_one(f32x16& od, int vb, bf16x8 pa0, bf16x8 pa1, bf16x8 pa2, bf16x8 pa3) {
;   const s16x4 l0 = tr_read<v_rd_off(D0, 0, 0)>(vb), h0 = tr_read<v_rd_off(D0, 0, 1)>(vb), l1 = tr_read<v_rd_off(D0, 1, 0)>(vb), h1 = tr_read<v_rd_off(D0, 1, 1)>(vb);
;   const s16x4 l2 = tr_read<v_rd_off(D0, 2, 0)>(vb), h2 = tr_read<v_rd_off(D0, 2, 1)>(vb), l3 = tr_read<v_rd_off(D0, 3, 0)>(vb), h3 = tr_read<v_rd_off(D0, 3, 1)>(vb);
;   asm volatile("s_waitcnt lgkmcnt(0)" ::: "memory"); SBAR();
;   od = __builtin_amdgcn_mfma_f32_32x32x16_bf16(pa0, ATT_PK(l0, h0), od, 0, 0, 0);
;   od = __builtin_amdgcn_mfma_f32_32x32x16_bf16(pa1, ATT_PK(l1, h1), od, 0, 0, 0);
;   od = __builtin_amdgcn_mfma_f32_32x32x16_bf16(pa2, ATT_PK(l2, h2), od, 0, 0, 0);
;   od = __builtin_amdgcn_mfma_f32_32x32x16_bf16(pa3, ATT_PK(l3, h3), od, 0, 0, 0);
; }
; __device__ __forceinline__ void pv_d0(f32x16* o, int vb, bf16x8 pa0, bf16x8 pa1, bf16x8 pa2, bf16x8 pa3) {
;   pv_one<0>(o[0], vb, pa0, pa1, pa2, pa3); pv_one<1>(o[1], vb, pa0, pa1, pa2, pa3); pv_one<2>(o[2], vb, pa0, pa1, pa2, pa3); pv_one<3>(o[3], vb, pa0, pa1, pa2, pa3);
; template <bool FAST> __device__ __forceinline__ void attn_dense_body(const bf16_t* __restrict__ Qb, const bf16_t* __restrict__ Kh, const bf16_t* __restrict__ Vh, ...
;     ...
;     pv_d0(o, vb0, pa0, pa1, pa2, pa3); psm<FAST>(pB0, pB1, m_reg, mnB, alB);
;     __syncthreads(); SWAIT(); SWRITE(0, SE);
;     if constexpr (!FAST) RESC(alB); __syncthreads();
;     SBAR(); qkt(pA0, pA1, K_lds, qr, r32, hi);
;     fsm<FAST>(pB0, pB1, alB, l_reg, pa0, pa1, pa2, pa3); SBAR();
;     if (j + 3 < NT) SLOAD(SE, (j + 3) * KVBLK); SBAR();
;     pv_d0(o, vb0 + (int)SHM_V, pa0, pa1, pa2, pa3); psm<FAST>(pA0, pA1, m_reg, mnA, alA);
	v_mfma_f32_32x32x16_bf16 v[18:33], v[66:69], v[198:201], v[18:33]
	ds_read_b64_tr_b16 v[198:199], v180 offset:1024
	ds_read_b64_tr_b16 v[200:201], v180 offset:3072
	v_add_f32_e32 v202, v243, v202
	v_exp_f32_e32 v243, v102
	global_load_dwordx4 v[168:171], v[168:169], off offset:1024
	v_addc_co_u32_e32 v173, vcc, 0, v187, vcc
	v_add_co_u32_e32 v176, vcc, s3, v186
	s_waitcnt lgkmcnt(6)
	v_mfma_f32_32x32x16_bf16 v[18:33], v[70:73], v[226:229], v[18:33]
	ds_read_b64_tr_b16 v[226:227], v180 offset:5120
	ds_read_b64_tr_b16 v[228:229], v180 offset:7168
	v_add_f32_e32 v202, v244, v202
	v_exp_f32_e32 v244, v103
	global_load_dwordx4 v[172:175], v[172:173], off
	v_addc_co_u32_e32 v177, vcc, 0, v187, vcc
	s_waitcnt lgkmcnt(6)
	v_mfma_f32_32x32x16_bf16 v[18:33], v[74:77], v[230:233], v[18:33]
	ds_read_b64_tr_b16 v[230:231], v180 offset:9216
	ds_read_b64_tr_b16 v[232:233], v180 offset:11264
	v_add_f32_e32 v202, v245, v202
	v_exp_f32_e32 v245, v104
	v_add_f32_e32 v202, v246, v202
	v_exp_f32_e32 v246, v105
	global_load_dwordx4 v[176:179], v[176:177], off
	s_waitcnt lgkmcnt(6)
	v_mfma_f32_32x32x16_bf16 v[18:33], v[78:81], v[234:237], v[18:33]
	ds_read_b64_tr_b16 v[234:235], v180 offset:13312
	ds_read_b64_tr_b16 v[236:237], v180 offset:15360
	v_add_f32_e32 v202, v247, v202
	v_exp_f32_e32 v247, v106
	v_add_f32_e32 v202, v248, v202
	v_exp_f32_e32 v248, v107
	s_waitcnt lgkmcnt(6)
	v_mfma_f32_32x32x16_bf16 v[34:49], v[66:69], v[198:201], v[34:49]
	ds_read_b64_tr_b16 v[198:199], v180 offset:1536
	ds_read_b64_tr_b16 v[200:201], v180 offset:3584
	v_add_f32_e32 v202, v249, v202
	v_exp_f32_e32 v249, v108
	v_add_f32_e32 v202, v250, v202
	v_exp_f32_e32 v250, v109
	s_waitcnt lgkmcnt(6)
	v_mfma_f32_32x32x16_bf16 v[34:49], v[70:73], v[226:229], v[34:49]
	ds_read_b64_tr_b16 v[226:227], v180 offset:5632
	ds_read_b64_tr_b16 v[228:229], v180 offset:7680
	v_add_f32_e32 v202, v251, v202
	v_exp_f32_e32 v251, v110
	v_add_f32_e32 v202, v252, v202
	v_exp_f32_e32 v252, v111
	s_waitcnt lgkmcnt(6)
	v_mfma_f32_32x32x16_bf16 v[34:49], v[74:77], v[230:233], v[34:49]
	ds_read_b64_tr_b16 v[230:231], v180 offset:9728
	ds_read_b64_tr_b16 v[232:233], v180 offset:11776
	v_add_f32_e32 v202, v182, v202
	v_exp_f32_e32 v182, v112
	v_add_f32_e32 v202, v183, v202
	v_exp_f32_e32 v183, v113
	s_waitcnt lgkmcnt(6)
	v_mfma_f32_32x32x16_bf16 v[34:49], v[78:81], v[234:237], v[34:49]
	ds_read_b64_tr_b16 v[234:235], v180 offset:13824
	ds_read_b64_tr_b16 v[236:237], v180 offset:15872
	v_mov_b32_e32 v238, v202
	s_waitcnt lgkmcnt(0)
	v_mfma_f32_32x32x16_bf16 v[50:65], v[66:69], v[198:201], v[50:65]
	s_barrier
	ds_write_b128 v217, v[148:151] offset:0
	ds_write_b128 v218, v[152:155] offset:0
	ds_read_b128 v[156:159], v221 offset:32768
	ds_read_b128 v[160:163], v221 offset:40960
	v_permlane32_swap_b32_e32 v202, v238
	v_mfma_f32_32x32x16_bf16 v[50:65], v[70:73], v[226:229], v[50:65]
	v_add_f32_e32 v238, v202, v238
	v_add_f32_e32 v1, v1, v238
	ds_read_b128 v[148:151], v223 offset:32768
	ds_read_b128 v[152:155], v223 offset:40960
	v_mfma_f32_32x32x16_bf16 v[50:65], v[74:77], v[230:233], v[50:65]
	v_mfma_f32_32x32x16_bf16 v[50:65], v[78:81], v[234:237], v[50:65]
	ds_read_b128 v[184:187], v219 offset:32768
	ds_read_b128 v[190:193], v219 offset:40960
	s_waitcnt lgkmcnt(5)
	v_mfma_f32_32x32x16_bf16 v[98:113], v[156:159], v[144:147], 0
	v_exp_f32_e32 v229, v82
	v_exp_f32_e32 v230, v83
	v_add_f32_e32 v202, 0, v239
	s_waitcnt lgkmcnt(4)
	v_mfma_f32_32x32x16_bf16 v[66:81], v[160:163], v[144:147], 0
	ds_read_b128 v[156:159], v216 offset:32768
	ds_read_b128 v[160:163], v216 offset:40960
	v_exp_f32_e32 v231, v84
	v_exp_f32_e32 v233, v85
	v_add_f32_e32 v202, v240, v202
	s_waitcnt lgkmcnt(5)
	v_mfma_f32_32x32x16_bf16 v[98:113], v[148:151], v[140:143], v[98:113]
	v_exp_f32_e32 v234, v86
	v_exp_f32_e32 v236, v87
	v_add_f32_e32 v202, v241, v202
	s_waitcnt lgkmcnt(4)
	v_mfma_f32_32x32x16_bf16 v[66:81], v[152:155], v[140:143], v[66:81]
	ds_read_b128 v[148:151], v215 offset:32768
	ds_read_b128 v[152:155], v215 offset:40960
	v_exp_f32_e32 v232, v88
	v_exp_f32_e32 v235, v89
	v_add_f32_e32 v202, v242, v202
	s_waitcnt lgkmcnt(5)
	v_mfma_f32_32x32x16_bf16 v[98:113], v[184:187], v[136:139], v[98:113]
	v_cvt_pk_bf16_f32 v82, v239, v240
	v_cvt_pk_bf16_f32 v83, v241, v242
	v_cvt_pk_bf16_f32 v84, v243, v244
	v_cvt_pk_bf16_f32 v85, v245, v246
	v_add_f32_e32 v202, v243, v202
	s_waitcnt lgkmcnt(4)
	v_mfma_f32_32x32x16_bf16 v[66:81], v[190:193], v[136:139], v[66:81]
	ds_read_b128 v[184:187], v214 offset:32768
	ds_read_b128 v[190:193], v214 offset:40960
	v_add_f32_e32 v202, v244, v202
	v_add_f32_e32 v202, v245, v202
	v_permlane32_swap_b32_e32 v82, v84
	v_permlane32_swap_b32_e32 v83, v85
	v_exp_f32_e32 v199, v90
	s_waitcnt lgkmcnt(5)
	v_mfma_f32_32x32x16_bf16 v[98:113], v[156:159], v[132:135], v[98:113]
	v_exp_f32_e32 v200, v91
	v_add_f32_e32 v202, v246, v202
	v_add_f32_e32 v202, v247, v202
	v_add_f32_e32 v202, v248, v202
	s_waitcnt lgkmcnt(4)
	v_mfma_f32_32x32x16_bf16 v[66:81], v[160:163], v[132:135], v[66:81]
	ds_read_b128 v[156:159], v213 offset:32768
	ds_read_b128 v[160:163], v213 offset:40960
	v_cvt_pk_bf16_f32 v86, v247, v248
	v_cvt_pk_bf16_f32 v87, v249, v250
	v_cvt_pk_bf16_f32 v88, v251, v252
	v_cvt_pk_bf16_f32 v89, v182, v183
	v_add_f32_e32 v202, v249, v202
	s_waitcnt lgkmcnt(5)
	v_mfma_f32_32x32x16_bf16 v[98:113], v[148:151], v[128:131], v[98:113]
	v_add_f32_e32 v202, v250, v202
	v_add_f32_e32 v202, v251, v202
	v_permlane32_swap_b32_e32 v86, v88
	v_permlane32_swap_b32_e32 v87, v89
	s_waitcnt vmcnt(0)
	ds_write_b128 v220, v[172:175] offset:49152
	ds_write_b128 v222, v[176:179] offset:49152
	s_waitcnt lgkmcnt(6)
; #define SBAR() __builtin_amdgcn_sched_barrier(0)
; #define SLOAD(i, k0) do { const char* vb_ = (const char*)Vh + (size_t)(k0) * (LDV * 2); const char* kb_ = (const char*)Kh + (size_t)(k0) * (LDKK * 2); \
;     sr_[i].vs0 = *(const bf16x8*)(vb_ + voff); sr_[i].vs1 = *(const bf16x8*)(vb_ + 32 * LDV * 2 + voff); \
;     sr_[i].ks0 = *(const bf16x8*)(kb_ + koff); sr_[i].ks1 = *(const bf16x8*)(kb_ + 32 * LDKK * 2 + koff); } while (0)
; #define SWAIT() asm volatile("s_waitcnt vmcnt(4)" ::: "memory")
; template <int D0> __device__ __forceinline__ void pv_one(f32x16& od, int vb, bf16x8 pa0, bf16x8 pa1, bf16x8 pa2, bf16x8 pa3) {
;   const s16x4 l0 = tr_read<v_rd_off(D0, 0, 0)>(vb), h0 = tr_read<v_rd_off(D0, 0, 1)>(vb), l1 = tr_read<v_rd_off(D0, 1, 0)>(vb), h1 = tr_read<v_rd_off(D0, 1, 1)>(vb);
;   const s16x4 l2 = tr_read<v_rd_off(D0, 2, 0)>(vb), h2 = tr_read<v_rd_off(D0, 2, 1)>(vb), l3 = tr_read<v_rd_off(D0, 3, 0)>(vb), h3 = tr_read<v_rd_off(D0, 3, 1)>(vb);
;   asm volatile("s_waitcnt lgkmcnt(0)" ::: "memory"); SBAR();
;   od = __builtin_amdgcn_mfma_f32_32x32x16_bf16(pa0, ATT_PK(l0, h0), od, 0, 0, 0);
;   od = __builtin_amdgcn_mfma_f32_32x32x16_bf16(pa1, ATT_PK(l1, h1), od, 0, 0, 0);
;   od = __builtin_amdgcn_mfma_f32_32x32x16_bf16(pa2, ATT_PK(l2, h2), od, 0, 0, 0);
;   od = __builtin_amdgcn_mfma_f32_32x32x16_bf16(pa3, ATT_PK(l3, h3), od, 0, 0, 0);
; }
; __device__ __forceinline__ void pv_d0(f32x16* o, int vb, bf16x8 pa0, bf16x8 pa1, bf16x8 pa2, bf16x8 pa3) {
;   pv_one<0>(o[0], vb, pa0, pa1, pa2, pa3); pv_one<1>(o[1], vb, pa0, pa1, pa2, pa3); pv_one<2>(o[2], vb, pa0, pa1, pa2, pa3); pv_one<3>(o[3], vb, pa0, pa1, pa2, pa3);
; template <bool FAST> __device__ __forceinline__ void attn_dense_body(const bf16_t* __restrict__ Qb, const bf16_t* __restrict__ Kh, const bf16_t* __restrict__ Vh, ...
;     ...
;     SBAR(); qkt(pA0, pA1, K_lds, qr, r32, hi);
;     fsm<FAST>(pB0, pB1, alB, l_reg, pa0, pa1, pa2, pa3); SBAR();
;     if (j + 3 < NT) SLOAD(SE, (j + 3) * KVBLK); SBAR();
;     pv_d0(o, vb0 + (int)SHM_V, pa0, pa1, pa2, pa3); psm<FAST>(pA0, pA1, m_reg, mnA, alA);
;     __syncthreads(); SWAIT(); SWRITE(1, SO);
;     if constexpr (!FAST) RESC(alA); __syncthreads();
;   }
	v_mfma_f32_32x32x16_bf16 v[66:81], v[152:155], v[128:131], v[66:81]
	ds_read_b128 v[148:151], v224 offset:32768
	ds_read_b128 v[152:155], v224 offset:40960
	v_exp_f32_e32 v201, v92
	v_exp_f32_e32 v227, v93
	v_add_f32_e32 v202, v252, v202
	s_waitcnt lgkmcnt(7)
	v_mfma_f32_32x32x16_bf16 v[98:113], v[184:187], v[124:127], v[98:113]
	v_exp_f32_e32 v198, v94
	v_exp_f32_e32 v225, v95
	v_add_f32_e32 v202, v182, v202
	s_waitcnt lgkmcnt(6)
	v_mfma_f32_32x32x16_bf16 v[66:81], v[190:193], v[124:127], v[66:81]
	v_exp_f32_e32 v226, v96
	v_exp_f32_e32 v228, v97
	v_add_f32_e32 v202, v183, v202
	s_waitcnt lgkmcnt(5)
	v_mfma_f32_32x32x16_bf16 v[98:113], v[156:159], v[120:123], v[98:113]
	v_cvt_pk_bf16_f32 v90, v229, v230
	v_cvt_pk_bf16_f32 v91, v231, v233
	v_cvt_pk_bf16_f32 v92, v234, v236
	v_cvt_pk_bf16_f32 v93, v232, v235
	s_waitcnt lgkmcnt(4)
	v_mfma_f32_32x32x16_bf16 v[66:81], v[160:163], v[120:123], v[66:81]
	v_cvt_pk_bf16_f32 v94, v199, v200
	v_cvt_pk_bf16_f32 v95, v201, v227
	v_permlane32_swap_b32_e32 v90, v92
	v_permlane32_swap_b32_e32 v91, v93
	ds_read_b64_tr_b16 v[240:241], v115 offset:0
	ds_read_b64_tr_b16 v[242:243], v115 offset:2048
	s_waitcnt lgkmcnt(3)
	v_mfma_f32_32x32x16_bf16 v[98:113], v[148:151], v[116:119], v[98:113]
	v_cvt_pk_bf16_f32 v96, v198, v225
	v_cvt_pk_bf16_f32 v97, v226, v228
	ds_read_b64_tr_b16 v[244:245], v115 offset:4096
	ds_read_b64_tr_b16 v[246:247], v115 offset:6144
	ds_read_b64_tr_b16 v[248:249], v115 offset:8192
	ds_read_b64_tr_b16 v[250:251], v115 offset:10240
	s_waitcnt lgkmcnt(6)
	v_mfma_f32_32x32x16_bf16 v[66:81], v[152:155], v[116:119], v[66:81]
	ds_read_b64_tr_b16 v[190:191], v115 offset:12288
	ds_read_b64_tr_b16 v[192:193], v115 offset:14336
	v_permlane32_swap_b32_e32 v94, v96
	v_permlane32_swap_b32_e32 v95, v97
	s_cmpk_gt_u32 s8, 0x7c
	s_cbranch_scc1 .Lattn_h2c_last
	s_waitcnt lgkmcnt(6)
	v_mfma_f32_32x32x16_bf16 v[2:17], v[82:85], v[240:243], v[2:17]
	ds_read_b64_tr_b16 v[240:241], v115 offset:512
	ds_read_b64_tr_b16 v[242:243], v115 offset:2560
	v_add_f32_e32 v202, v229, v202
	v_exp_f32_e32 v229, v98
	v_lshl_add_u64 v[188:189], v[196:197], 0, s[48:49]
	v_lshl_add_u64 v[186:187], v[194:195], 0, s[48:49]
	s_waitcnt lgkmcnt(6)
	v_mfma_f32_32x32x16_bf16 v[2:17], v[86:89], v[244:247], v[2:17]
	ds_read_b64_tr_b16 v[244:245], v115 offset:4608
	ds_read_b64_tr_b16 v[246:247], v115 offset:6656
	v_add_f32_e32 v202, v230, v202
	v_exp_f32_e32 v230, v99
	v_add_co_u32_e32 v148, vcc, 0x4d684000, v188
	s_waitcnt lgkmcnt(6)
	v_mfma_f32_32x32x16_bf16 v[2:17], v[90:93], v[248:251], v[2:17]
	ds_read_b64_tr_b16 v[248:249], v115 offset:8704
	ds_read_b64_tr_b16 v[250:251], v115 offset:10752
	v_add_f32_e32 v202, v231, v202
	v_exp_f32_e32 v231, v100
	v_addc_co_u32_e32 v149, vcc, 0, v189, vcc
	v_add_co_u32_e32 v152, vcc, 0x4d714000, v188
	s_waitcnt lgkmcnt(6)
	v_mfma_f32_32x32x16_bf16 v[2:17], v[94:97], v[190:193], v[2:17]
	ds_read_b64_tr_b16 v[190:191], v115 offset:12800
	ds_read_b64_tr_b16 v[192:193], v115 offset:14848
	v_add_f32_e32 v202, v233, v202
	v_exp_f32_e32 v233, v101
	global_load_dwordx4 v[148:151], v[148:149], off offset:1024
	v_addc_co_u32_e32 v153, vcc, 0, v189, vcc
	v_add_co_u32_e32 v156, vcc, 0x5f240000, v186
	s_waitcnt lgkmcnt(6)
	v_mfma_f32_32x32x16_bf16 v[18:33], v[82:85], v[240:243], v[18:33]
	ds_read_b64_tr_b16 v[240:241], v115 offset:1024
	ds_read_b64_tr_b16 v[242:243], v115 offset:3072
	v_add_f32_e32 v202, v234, v202
	v_exp_f32_e32 v234, v102
	global_load_dwordx4 v[152:155], v[152:153], off offset:1024
	v_addc_co_u32_e32 v157, vcc, 0, v187, vcc
	v_add_co_u32_e32 v160, vcc, 0x5f248000, v186
	s_waitcnt lgkmcnt(6)
	v_mfma_f32_32x32x16_bf16 v[18:33], v[86:89], v[244:247], v[18:33]
	ds_read_b64_tr_b16 v[244:245], v115 offset:5120
	ds_read_b64_tr_b16 v[246:247], v115 offset:7168
	v_add_f32_e32 v202, v236, v202
	v_exp_f32_e32 v236, v103
	global_load_dwordx4 v[156:159], v[156:157], off
	v_addc_co_u32_e32 v161, vcc, 0, v187, vcc
	s_waitcnt lgkmcnt(6)
	v_mfma_f32_32x32x16_bf16 v[18:33], v[90:93], v[248:251], v[18:33]
	ds_read_b64_tr_b16 v[248:249], v115 offset:9216
	ds_read_b64_tr_b16 v[250:251], v115 offset:11264
	v_add_f32_e32 v202, v232, v202
	v_exp_f32_e32 v232, v104
	v_add_f32_e32 v202, v235, v202
	v_exp_f32_e32 v235, v105
	global_load_dwordx4 v[160:163], v[160:161], off
	s_waitcnt lgkmcnt(6)
	v_mfma_f32_32x32x16_bf16 v[18:33], v[94:97], v[190:193], v[18:33]
	ds_read_b64_tr_b16 v[190:191], v115 offset:13312
	ds_read_b64_tr_b16 v[192:193], v115 offset:15360
	v_add_f32_e32 v202, v199, v202
	v_exp_f32_e32 v199, v106
	v_add_f32_e32 v202, v200, v202
	v_exp_f32_e32 v200, v107
	s_waitcnt lgkmcnt(6)
	v_mfma_f32_32x32x16_bf16 v[34:49], v[82:85], v[240:243], v[34:49]
	ds_read_b64_tr_b16 v[240:241], v115 offset:1536
	ds_read_b64_tr_b16 v[242:243], v115 offset:3584
	v_add_f32_e32 v202, v201, v202
	v_exp_f32_e32 v201, v108
	v_add_f32_e32 v202, v227, v202
	v_exp_f32_e32 v227, v109
	s_waitcnt lgkmcnt(6)
	v_mfma_f32_32x32x16_bf16 v[34:49], v[86:89], v[244:247], v[34:49]
	ds_read_b64_tr_b16 v[244:245], v115 offset:5632
	ds_read_b64_tr_b16 v[246:247], v115 offset:7680
	v_add_f32_e32 v202, v198, v202
	v_exp_f32_e32 v198, v110
	v_add_f32_e32 v202, v225, v202
	v_exp_f32_e32 v225, v111
	s_waitcnt lgkmcnt(6)
	v_mfma_f32_32x32x16_bf16 v[34:49], v[90:93], v[248:251], v[34:49]
	ds_read_b64_tr_b16 v[248:249], v115 offset:9728
	ds_read_b64_tr_b16 v[250:251], v115 offset:11776
	v_add_f32_e32 v202, v226, v202
	v_exp_f32_e32 v226, v112
	v_add_f32_e32 v202, v228, v202
	v_exp_f32_e32 v228, v113
	s_waitcnt lgkmcnt(6)
	v_mfma_f32_32x32x16_bf16 v[34:49], v[94:97], v[190:193], v[34:49]
	ds_read_b64_tr_b16 v[190:191], v115 offset:13824
	ds_read_b64_tr_b16 v[192:193], v115 offset:15872
	v_mov_b32_e32 v238, v202
	s_waitcnt lgkmcnt(0)
	v_mfma_f32_32x32x16_bf16 v[50:65], v[82:85], v[240:243], v[50:65]
	s_barrier
	ds_write_b128 v217, v[164:167] offset:16384
	ds_write_b128 v218, v[168:171] offset:16384
	ds_read_b128 v[172:175], v221 offset:49152
	ds_read_b128 v[176:179], v221 offset:57344
	v_permlane32_swap_b32_e32 v202, v238
	v_mfma_f32_32x32x16_bf16 v[50:65], v[86:89], v[244:247], v[50:65]
	v_add_f32_e32 v238, v202, v238
	v_add_f32_e32 v1, v1, v238
	ds_read_b128 v[164:167], v223 offset:49152
	ds_read_b128 v[168:171], v223 offset:57344
	v_mfma_f32_32x32x16_bf16 v[50:65], v[90:93], v[248:251], v[50:65]
	v_mfma_f32_32x32x16_bf16 v[50:65], v[94:97], v[190:193], v[50:65]
	v_lshl_add_u64 v[194:195], v[194:195], 0, s[30:31]
	v_lshl_add_u64 v[196:197], v[196:197], 0, s[80:81]
	s_add_i32 s8, s8, 2
	s_branch .Lattn_h1
